# attention: static s_setprio 1 for waves 4-7 during the attention phase
# speedup vs baseline: 1.0035x; 1.0035x over previous
.LBB0_409:
	s_and_b64 vcc, exec, s[0:1]
	s_cbranch_vccz .LBB0_492
	v_readlane_b32 s0, v255, 12
	s_cmpk_gt_i32 s0, 0x7ff
	s_cbranch_scc1 .LBB0_492
	s_mov_b32 s24, m0
	v_readfirstlane_b32 s4, v198
	v_readlane_b32 s38, v255, 12
	s_lshr_b32 s27, s4, 6
	s_lshl_b32 s16, s27, 10
	s_lshr_b32 s2, s27, 2
	s_cmp_eq_u32 s2, 1
	s_cbranch_scc0 .Lat2_noprio
	s_setprio 1
.Lat2_noprio:
	v_and_b32_e32 v228, 31, v246
	v_lshrrev_b32_e32 v229, 5, v246
	v_lshlrev_b32_e32 v200, 10, v246
	s_lshl_b32 s4, s27, 4
	v_add_u32_e32 v200, s4, v200
	v_lshrrev_b32_e32 v230, 2, v246
	s_and_b32 s4, s27, 3
	s_lshl_b32 s4, s4, 4
	v_add_u32_e32 v230, s4, v230
	v_lshlrev_b32_e32 v230, 10, v230
	v_and_b32_e32 v231, 3, v246
	v_lshlrev_b32_e32 v231, 4, v231
	s_lshr_b32 s4, s27, 2
	s_lshl_b32 s4, s4, 6
	v_add3_u32 v201, v230, v231, s4
	v_add_u32_e32 v202, 0x80, v201
	s_lshl_b32 s4, s27, 5
	v_add_u32_e32 v230, s4, v228
	v_lshlrev_b32_e32 v225, 10, v230
	v_lshl_add_u32 v225, v229, 4, v225
	v_lshlrev_b32_e32 v231, 2, v229
	v_sub_u32_e32 v218, v230, v231
	v_lshlrev_b32_e32 v203, 10, v229
	v_lshl_add_u32 v203, v228, 4, v203
	v_bfe_u32 v230, v246, 4, 1
	v_lshlrev_b32_e32 v230, 5, v230
	v_and_b32_e32 v231, 3, v246
	v_lshl_add_u32 v230, v231, 3, v230
	v_bfe_u32 v231, v246, 2, 2
	v_lshl_add_u32 v231, v229, 2, v231
	v_lshl_add_u32 v230, v231, 6, v230
	v_add_u32_e32 v204, 0x8000, v230
	s_lshl_b32 s4, s27, 8
	s_add_i32 s4, s4, 0x18000
	v_lshl_add_u32 v220, v228, 2, s4
	v_lshl_add_u32 v221, v229, 4, s4
	s_lshl_b32 s4, s27, 11
	s_add_i32 s4, s4, 0x18800
	v_lshlrev_b32_e32 v230, 8, v229
	v_lshl_add_u32 v230, v228, 1, v230
	v_add_u32_e32 v222, s4, v230
	v_lshrrev_b32_e32 v230, 2, v246
	v_and_b32_e32 v231, 3, v246
	v_lshlrev_b32_e32 v223, 6, v230
	v_lshl_add_u32 v223, v231, 4, v223
	v_add_u32_e32 v223, s4, v223
	s_lshl_b32 s4, s27, 5
	v_add_u32_e32 v230, s4, v230
	v_lshlrev_b32_e32 v224, 11, v230
	v_lshl_add_u32 v224, v231, 4, v224
	v_mov_b32_e32 v219, 0xff800000
	s_mov_b32 s26, 0

.Lat2_done_5:
	s_setprio 0
	s_mov_b32 m0, s24
	s_waitcnt lgkmcnt(0)
	s_barrier
